# stack32 + deferred-weights loads in P1 with cache policy sc1 nt (that path gates the P1->P2 barrier)
# baseline (speedup 1.0000x reference)
.LBB0_341:
	s_cmpk_gt_i32 s19, 0xbff
	s_mov_b64 s[4:5], -1
	s_cbranch_scc0 .LBB0_343
	s_bfe_u32 s12, s19, 0x10007
	s_and_b32 s4, s19, 0x7fffff00
	s_cmpk_eq_i32 s4, 0xc00
	s_cselect_b32 s4, 40, 64
	s_cselect_b32 s13, s25, 0x8710000
	s_add_u32 s4, s80, s4
	s_addc_u32 s5, s81, 0
	s_load_dwordx2 s[4:5], s[4:5], 0x0
	s_lshl_b32 s14, s12, 21
	v_mov_b32_e32 v69, v67
	s_waitcnt lgkmcnt(0)
	s_add_u32 s4, s4, s14
	s_addc_u32 s5, s5, 0
	s_and_b32 s14, s21, 0xc0
	s_add_u32 s13, s10, s13
	v_or_b32_e32 v2, s14, v73
	s_addc_u32 s15, s11, 0
	s_and_b32 s35, s23, 0x7c0
	v_or_b32_e32 v4, s35, v74
	v_lshlrev_b32_e32 v66, 2, v2
	v_lshl_add_u64 v[2:3], s[4:5], 0, v[66:67]
	v_lshlrev_b32_e32 v66, 10, v4
	v_lshl_add_u64 v[62:63], v[2:3], 0, v[66:67]
	v_add_co_u32_e32 v10, vcc, s26, v62
	global_load_dwordx4 v[2:5], v[62:63], off sc1 nt
	s_nop 0
	v_addc_co_u32_e32 v11, vcc, 0, v63, vcc
	v_add_co_u32_e32 v18, vcc, s27, v62
	global_load_dwordx4 v[6:9], v[10:11], off offset:-4096 sc1 nt
	s_nop 0
	global_load_dwordx4 v[10:13], v[10:11], off sc1 nt
	v_addc_co_u32_e32 v19, vcc, 0, v63, vcc
	v_add_co_u32_e32 v26, vcc, s28, v62
	global_load_dwordx4 v[14:17], v[18:19], off offset:-4096 sc1 nt
	s_nop 0
	global_load_dwordx4 v[18:21], v[18:19], off sc1 nt
	v_addc_co_u32_e32 v27, vcc, 0, v63, vcc
	v_add_co_u32_e32 v34, vcc, s29, v62
	global_load_dwordx4 v[22:25], v[26:27], off offset:-4096 sc1 nt
	s_nop 0
	global_load_dwordx4 v[26:29], v[26:27], off sc1 nt
	v_addc_co_u32_e32 v35, vcc, 0, v63, vcc
	v_add_co_u32_e32 v42, vcc, s30, v62
	global_load_dwordx4 v[30:33], v[34:35], off offset:-4096 sc1 nt
	s_nop 0
	global_load_dwordx4 v[34:37], v[34:35], off sc1 nt
	v_addc_co_u32_e32 v43, vcc, 0, v63, vcc
	v_add_co_u32_e32 v50, vcc, s31, v62
	global_load_dwordx4 v[38:41], v[42:43], off offset:-4096 sc1 nt
	s_nop 0
	global_load_dwordx4 v[42:45], v[42:43], off sc1 nt
	v_addc_co_u32_e32 v51, vcc, 0, v63, vcc
	v_add_co_u32_e32 v58, vcc, s33, v62
	global_load_dwordx4 v[46:49], v[50:51], off offset:-4096 sc1 nt
	s_nop 0
	global_load_dwordx4 v[50:53], v[50:51], off sc1 nt
	v_addc_co_u32_e32 v59, vcc, 0, v63, vcc
	global_load_dwordx4 v[54:57], v[58:59], off offset:-4096 sc1 nt
	s_nop 0
	global_load_dwordx4 v[58:61], v[58:59], off sc1 nt
	v_add_co_u32_e32 v62, vcc, s34, v62
	s_lshl_b32 s4, s12, 8
	s_nop 0
	v_addc_co_u32_e32 v63, vcc, 0, v63, vcc
	global_load_dwordx4 v[62:65], v[62:63], off sc1 nt
	s_or_b32 s12, s4, s14
	s_lshl_b32 s4, s35, 1
	s_add_u32 s4, s13, s4
	s_addc_u32 s5, s15, 0
	s_waitcnt vmcnt(15)
	ds_write2_b32 v75, v2, v3 offset1:1
	ds_write2_b32 v75, v4, v5 offset0:2 offset1:3
	s_waitcnt vmcnt(14)
	ds_write2_b32 v87, v6, v7 offset1:1
	ds_write2_b32 v88, v8, v9 offset1:1
	s_waitcnt vmcnt(13)
	ds_write2_b32 v89, v10, v11 offset1:1
	ds_write2_b32 v90, v12, v13 offset1:1
	s_waitcnt vmcnt(12)
	ds_write2_b32 v91, v14, v15 offset1:1
	ds_write2_b32 v92, v16, v17 offset1:1
	s_waitcnt vmcnt(11)
	ds_write2_b32 v93, v18, v19 offset1:1
	ds_write2_b32 v94, v20, v21 offset1:1
	s_waitcnt vmcnt(10)
	ds_write2_b32 v95, v22, v23 offset1:1
	ds_write2_b32 v96, v24, v25 offset1:1
	s_waitcnt vmcnt(9)
	ds_write2_b32 v97, v26, v27 offset1:1
	ds_write2_b32 v98, v28, v29 offset1:1
	s_waitcnt vmcnt(8)
	ds_write2_b32 v99, v30, v31 offset1:1
	ds_write2_b32 v100, v32, v33 offset1:1
	s_waitcnt vmcnt(7)
	ds_write2_b32 v101, v34, v35 offset1:1
	ds_write2_b32 v102, v36, v37 offset1:1
	s_waitcnt vmcnt(6)
	ds_write2_b32 v103, v38, v39 offset1:1
	ds_write2_b32 v104, v40, v41 offset1:1
	s_waitcnt vmcnt(5)
	ds_write2_b32 v105, v42, v43 offset1:1
	ds_write2_b32 v106, v44, v45 offset1:1
	s_waitcnt vmcnt(4)
	ds_write2_b32 v107, v46, v47 offset1:1
	ds_write2_b32 v108, v48, v49 offset1:1
	s_waitcnt vmcnt(3)
	ds_write2_b32 v109, v50, v51 offset1:1
	ds_write2_b32 v110, v52, v53 offset1:1
	s_waitcnt vmcnt(2)
	ds_write2_b32 v111, v54, v55 offset1:1
	ds_write2_b32 v112, v56, v57 offset1:1
	s_waitcnt vmcnt(1)
	ds_write2_b32 v113, v58, v59 offset1:1
	ds_write2_b32 v114, v60, v61 offset1:1
	s_waitcnt vmcnt(0)
	ds_write2_b32 v115, v62, v63 offset1:1
	ds_write2_b32 v116, v64, v65 offset1:1
	s_waitcnt lgkmcnt(0)
	ds_read2_b32 v[6:7], v77 offset0:65 offset1:73
	ds_read2_b32 v[8:9], v77 offset1:8
	ds_read2_b32 v[10:11], v77 offset0:130 offset1:138
	ds_read2_b32 v[12:13], v77 offset0:195 offset1:203
	ds_read2_b32 v[14:15], v117 offset0:4 offset1:12
	ds_read2_b32 v[16:17], v117 offset0:69 offset1:77
	ds_read2_b32 v[18:19], v117 offset0:134 offset1:142
	ds_read2_b32 v[20:21], v117 offset0:199 offset1:207
	s_waitcnt lgkmcnt(6)
	v_cvt_pk_bf16_f32 v2, v8, v6
	v_or_b32_e32 v6, s12, v76
	v_lshl_add_u64 v[22:23], s[4:5], 0, v[68:69]
	v_lshlrev_b32_e32 v66, 12, v6
	s_waitcnt lgkmcnt(4)
	v_cvt_pk_bf16_f32 v3, v10, v12
	s_waitcnt lgkmcnt(2)
	v_cvt_pk_bf16_f32 v4, v14, v16
	s_waitcnt lgkmcnt(0)
	v_cvt_pk_bf16_f32 v5, v18, v20
	v_lshl_add_u64 v[24:25], v[22:23], 0, v[66:67]
	global_store_dwordx4 v[24:25], v[2:5], off
	v_or_b32_e32 v6, s12, v78
	v_lshlrev_b32_e32 v66, 12, v6
	v_cvt_pk_bf16_f32 v2, v9, v7
	v_cvt_pk_bf16_f32 v3, v11, v13
	v_cvt_pk_bf16_f32 v4, v15, v17
	v_cvt_pk_bf16_f32 v5, v19, v21
	ds_read2_b32 v[8:9], v77 offset0:81 offset1:89
	ds_read2_b32 v[10:11], v77 offset0:16 offset1:24
	ds_read2_b32 v[12:13], v77 offset0:146 offset1:154
	ds_read2_b32 v[14:15], v77 offset0:211 offset1:219
	ds_read2_b32 v[16:17], v117 offset0:20 offset1:28
	ds_read2_b32 v[18:19], v117 offset0:85 offset1:93
	ds_read2_b32 v[20:21], v117 offset0:150 offset1:158
	ds_read2_b32 v[24:25], v117 offset0:215 offset1:223
	v_lshl_add_u64 v[6:7], v[22:23], 0, v[66:67]
	global_store_dwordx4 v[6:7], v[2:5], off
	v_or_b32_e32 v6, s12, v80
	v_lshlrev_b32_e32 v66, 12, v6
	s_waitcnt lgkmcnt(6)
	v_cvt_pk_bf16_f32 v2, v10, v8
	s_waitcnt lgkmcnt(4)
	v_cvt_pk_bf16_f32 v3, v12, v14
	s_waitcnt lgkmcnt(2)
	v_cvt_pk_bf16_f32 v4, v16, v18
	s_waitcnt lgkmcnt(0)
	v_cvt_pk_bf16_f32 v5, v20, v24
	v_lshl_add_u64 v[6:7], v[22:23], 0, v[66:67]
	global_store_dwordx4 v[6:7], v[2:5], off
	v_or_b32_e32 v6, s12, v81
	v_lshlrev_b32_e32 v66, 12, v6
	v_cvt_pk_bf16_f32 v2, v11, v9
	v_cvt_pk_bf16_f32 v3, v13, v15
	v_cvt_pk_bf16_f32 v4, v17, v19
	v_cvt_pk_bf16_f32 v5, v21, v25
	ds_read2_b32 v[8:9], v77 offset0:32 offset1:40
	ds_read2_b32 v[10:11], v77 offset0:97 offset1:105
	ds_read2_b32 v[12:13], v77 offset0:162 offset1:170
	ds_read2_b32 v[14:15], v77 offset0:227 offset1:235
	ds_read2_b32 v[16:17], v117 offset0:36 offset1:44
	ds_read2_b32 v[18:19], v117 offset0:101 offset1:109
	ds_read2_b32 v[20:21], v117 offset0:166 offset1:174
	ds_read2_b32 v[24:25], v117 offset0:231 offset1:239
	v_lshl_add_u64 v[6:7], v[22:23], 0, v[66:67]
	global_store_dwordx4 v[6:7], v[2:5], off
	v_or_b32_e32 v6, s12, v82
	v_lshlrev_b32_e32 v66, 12, v6
	s_waitcnt lgkmcnt(6)
	v_cvt_pk_bf16_f32 v2, v8, v10
	s_waitcnt lgkmcnt(4)
	v_cvt_pk_bf16_f32 v3, v12, v14
	s_waitcnt lgkmcnt(2)
	v_cvt_pk_bf16_f32 v4, v16, v18
	s_waitcnt lgkmcnt(0)
	v_cvt_pk_bf16_f32 v5, v20, v24
	v_lshl_add_u64 v[6:7], v[22:23], 0, v[66:67]
	global_store_dwordx4 v[6:7], v[2:5], off
	v_or_b32_e32 v6, s12, v83
	v_lshlrev_b32_e32 v66, 12, v6
	v_cvt_pk_bf16_f32 v2, v9, v11
	v_cvt_pk_bf16_f32 v3, v13, v15
	v_cvt_pk_bf16_f32 v4, v17, v19
	v_cvt_pk_bf16_f32 v5, v21, v25
	ds_read2_b32 v[8:9], v77 offset0:48 offset1:56
	ds_read2_b32 v[10:11], v77 offset0:113 offset1:121
	ds_read2_b32 v[12:13], v77 offset0:178 offset1:186
	ds_read2_b32 v[14:15], v77 offset0:243 offset1:251
	ds_read2_b32 v[16:17], v117 offset0:52 offset1:60
	ds_read2_b32 v[18:19], v117 offset0:117 offset1:125
	ds_read2_b32 v[20:21], v117 offset0:182 offset1:190
	ds_read2_b32 v[24:25], v117 offset0:247 offset1:255
	v_lshl_add_u64 v[6:7], v[22:23], 0, v[66:67]
	global_store_dwordx4 v[6:7], v[2:5], off
	v_or_b32_e32 v6, s12, v84
	v_lshlrev_b32_e32 v66, 12, v6
	s_waitcnt lgkmcnt(6)
	v_cvt_pk_bf16_f32 v2, v8, v10
	s_waitcnt lgkmcnt(4)
	v_cvt_pk_bf16_f32 v3, v12, v14
	s_waitcnt lgkmcnt(2)
	v_cvt_pk_bf16_f32 v4, v16, v18
	s_waitcnt lgkmcnt(0)
	v_cvt_pk_bf16_f32 v5, v20, v24
	v_lshl_add_u64 v[6:7], v[22:23], 0, v[66:67]
	global_store_dwordx4 v[6:7], v[2:5], off
	v_or_b32_e32 v6, s12, v85
	v_lshlrev_b32_e32 v66, 12, v6
	v_cvt_pk_bf16_f32 v2, v9, v11
	v_cvt_pk_bf16_f32 v3, v13, v15
	v_cvt_pk_bf16_f32 v4, v17, v19
	v_cvt_pk_bf16_f32 v5, v21, v25
	v_lshl_add_u64 v[6:7], v[22:23], 0, v[66:67]
	global_store_dwordx4 v[6:7], v[2:5], off
	s_waitcnt lgkmcnt(0)
	s_mov_b64 s[4:5], 0
.LBB0_343:
	s_andn2_b64 vcc, exec, s[4:5]
	s_cbranch_vccnz .LBB0_340
	s_ashr_i32 s4, s19, 31
	s_lshr_b32 s4, s4, 22
	s_add_i32 s4, s19, s4
	s_ashr_i32 s12, s4, 10
	s_and_b32 s4, s4, 0xfffffc00
	s_ashr_i32 s13, s12, 31
	s_sub_i32 s37, s19, s4
	s_lshl_b64 s[4:5], s[12:13], 3
	s_add_u32 s4, s80, s4
	s_addc_u32 s5, s81, s5
	s_load_dwordx2 s[4:5], s[4:5], 0x60
	s_lshl_b32 s14, s12, 11
	s_sub_i32 s35, s21, s14
	s_andn2_b32 s35, s35, 63
	s_and_b32 s36, s23, 0x7c0
	v_or_b32_e32 v66, s35, v73
	s_cmp_gt_i32 s37, -1
	v_or_b32_e32 v2, s36, v74
	s_cselect_b64 s[14:15], -1, 0
	s_cmp_lt_i32 s37, 0
	s_waitcnt lgkmcnt(0)
	v_lshl_add_u64 v[70:71], v[66:67], 2, s[4:5]
	v_mov_b32_e32 v6, 0
	v_lshlrev_b32_e32 v66, 13, v2
	v_mov_b32_e32 v2, 0
	v_mov_b32_e32 v3, 0
	v_mov_b32_e32 v4, 0
	v_mov_b32_e32 v5, 0
	s_cbranch_scc1 .LBB0_346
	v_lshl_add_u64 v[2:3], v[70:71], 0, v[66:67]
	global_load_dwordx4 v[2:5], v[2:3], off sc1 nt
.LBB0_346:
	v_cndmask_b32_e64 v7, 0, 1, s[14:15]
	v_cmp_ne_u32_e64 s[4:5], 1, v7
	s_andn2_b64 vcc, exec, s[14:15]
	v_mov_b32_e32 v7, 0
	v_mov_b32_e32 v8, 0
	v_mov_b32_e32 v9, 0
	s_cbranch_vccnz .LBB0_348
	v_lshl_add_u64 v[6:7], v[70:71], 0, v[66:67]
	v_add_co_u32_e32 v6, vcc, 0x8000, v6
	s_nop 1
	v_addc_co_u32_e32 v7, vcc, 0, v7, vcc
	global_load_dwordx4 v[6:9], v[6:7], off sc1 nt
.LBB0_348:
	v_mov_b32_e32 v10, 0
	s_and_b64 vcc, exec, s[4:5]
	v_mov_b32_e32 v14, 0
	v_mov_b32_e32 v15, 0
	v_mov_b32_e32 v16, 0
	v_mov_b32_e32 v17, 0
	s_cbranch_vccnz .LBB0_350
	v_lshl_add_u64 v[12:13], v[70:71], 0, v[66:67]
	v_add_co_u32_e32 v12, vcc, 0x10000, v12
	s_nop 1
	v_addc_co_u32_e32 v13, vcc, 0, v13, vcc
	global_load_dwordx4 v[14:17], v[12:13], off sc1 nt
.LBB0_350:
	s_and_b64 vcc, exec, s[4:5]
	v_mov_b32_e32 v11, 0
	v_mov_b32_e32 v12, 0
	v_mov_b32_e32 v13, 0
	s_cbranch_vccnz .LBB0_352
	v_lshl_add_u64 v[10:11], v[70:71], 0, v[66:67]
	v_add_co_u32_e32 v10, vcc, 0x18000, v10
	s_nop 1
	v_addc_co_u32_e32 v11, vcc, 0, v11, vcc
	global_load_dwordx4 v[10:13], v[10:11], off sc1 nt
.LBB0_352:
	v_mov_b32_e32 v18, 0
	s_and_b64 vcc, exec, s[4:5]
	v_mov_b32_e32 v22, 0
	v_mov_b32_e32 v23, 0
	v_mov_b32_e32 v24, 0
	v_mov_b32_e32 v25, 0
	s_cbranch_vccnz .LBB0_354
	v_lshl_add_u64 v[20:21], v[70:71], 0, v[66:67]
	v_add_co_u32_e32 v20, vcc, 0x20000, v20
	s_nop 1
	v_addc_co_u32_e32 v21, vcc, 0, v21, vcc
	global_load_dwordx4 v[22:25], v[20:21], off sc1 nt
.LBB0_354:
	s_and_b64 vcc, exec, s[4:5]
	v_mov_b32_e32 v19, 0
	v_mov_b32_e32 v20, 0
	v_mov_b32_e32 v21, 0
	s_cbranch_vccnz .LBB0_356
	v_lshl_add_u64 v[18:19], v[70:71], 0, v[66:67]
	v_add_co_u32_e32 v18, vcc, 0x28000, v18
	s_nop 1
	v_addc_co_u32_e32 v19, vcc, 0, v19, vcc
	global_load_dwordx4 v[18:21], v[18:19], off sc1 nt
.LBB0_356:
	v_mov_b32_e32 v26, 0
	s_and_b64 vcc, exec, s[4:5]
	v_mov_b32_e32 v30, 0
	v_mov_b32_e32 v31, 0
	v_mov_b32_e32 v32, 0
	v_mov_b32_e32 v33, 0
	s_cbranch_vccnz .LBB0_358
	v_lshl_add_u64 v[28:29], v[70:71], 0, v[66:67]
	v_add_co_u32_e32 v28, vcc, 0x30000, v28
	s_nop 1
	v_addc_co_u32_e32 v29, vcc, 0, v29, vcc
	global_load_dwordx4 v[30:33], v[28:29], off sc1 nt
.LBB0_358:
	s_and_b64 vcc, exec, s[4:5]
	v_mov_b32_e32 v27, 0
	v_mov_b32_e32 v28, 0
	v_mov_b32_e32 v29, 0
	s_cbranch_vccnz .LBB0_360
	v_lshl_add_u64 v[26:27], v[70:71], 0, v[66:67]
	v_add_co_u32_e32 v26, vcc, 0x38000, v26
	s_nop 1
	v_addc_co_u32_e32 v27, vcc, 0, v27, vcc
	global_load_dwordx4 v[26:29], v[26:27], off sc1 nt
.LBB0_360:
	v_mov_b32_e32 v34, 0
	s_and_b64 vcc, exec, s[4:5]
	v_mov_b32_e32 v38, 0
	v_mov_b32_e32 v39, 0
	v_mov_b32_e32 v40, 0
	v_mov_b32_e32 v41, 0
	s_cbranch_vccnz .LBB0_362
	v_lshl_add_u64 v[36:37], v[70:71], 0, v[66:67]
	v_add_co_u32_e32 v36, vcc, 0x40000, v36
	s_nop 1
	v_addc_co_u32_e32 v37, vcc, 0, v37, vcc
	global_load_dwordx4 v[38:41], v[36:37], off sc1 nt
.LBB0_362:
	s_and_b64 vcc, exec, s[4:5]
	v_mov_b32_e32 v35, 0
	v_mov_b32_e32 v36, 0
	v_mov_b32_e32 v37, 0
	s_cbranch_vccnz .LBB0_364
	v_lshl_add_u64 v[34:35], v[70:71], 0, v[66:67]
	v_add_co_u32_e32 v34, vcc, 0x48000, v34
	s_nop 1
	v_addc_co_u32_e32 v35, vcc, 0, v35, vcc
	global_load_dwordx4 v[34:37], v[34:35], off sc1 nt
.LBB0_364:
	v_mov_b32_e32 v42, 0
	s_and_b64 vcc, exec, s[4:5]
	v_mov_b32_e32 v46, 0
	v_mov_b32_e32 v47, 0
	v_mov_b32_e32 v48, 0
	v_mov_b32_e32 v49, 0
	s_cbranch_vccnz .LBB0_366
	v_lshl_add_u64 v[44:45], v[70:71], 0, v[66:67]
	v_add_co_u32_e32 v44, vcc, 0x50000, v44
	s_nop 1
	v_addc_co_u32_e32 v45, vcc, 0, v45, vcc
	global_load_dwordx4 v[46:49], v[44:45], off sc1 nt
.LBB0_366:
	s_and_b64 vcc, exec, s[4:5]
	v_mov_b32_e32 v43, 0
	v_mov_b32_e32 v44, 0
	v_mov_b32_e32 v45, 0
	s_cbranch_vccnz .LBB0_368
	v_lshl_add_u64 v[42:43], v[70:71], 0, v[66:67]
	v_add_co_u32_e32 v42, vcc, 0x58000, v42
	s_nop 1
	v_addc_co_u32_e32 v43, vcc, 0, v43, vcc
	global_load_dwordx4 v[42:45], v[42:43], off sc1 nt
.LBB0_368:
	v_mov_b32_e32 v50, 0
	s_and_b64 vcc, exec, s[4:5]
	v_mov_b32_e32 v54, 0
	v_mov_b32_e32 v55, 0
	v_mov_b32_e32 v56, 0
	v_mov_b32_e32 v57, 0
	s_cbranch_vccnz .LBB0_370
	v_lshl_add_u64 v[52:53], v[70:71], 0, v[66:67]
	v_add_co_u32_e32 v52, vcc, 0x60000, v52
	s_nop 1
	v_addc_co_u32_e32 v53, vcc, 0, v53, vcc
	global_load_dwordx4 v[54:57], v[52:53], off sc1 nt
.LBB0_370:
	s_and_b64 vcc, exec, s[4:5]
	v_mov_b32_e32 v51, 0
	v_mov_b32_e32 v52, 0
	v_mov_b32_e32 v53, 0
	s_cbranch_vccnz .LBB0_372
	v_lshl_add_u64 v[50:51], v[70:71], 0, v[66:67]
	v_add_co_u32_e32 v50, vcc, 0x68000, v50
	s_nop 1
	v_addc_co_u32_e32 v51, vcc, 0, v51, vcc
	global_load_dwordx4 v[50:53], v[50:51], off sc1 nt
.LBB0_372:
	v_mov_b32_e32 v58, 0
	s_and_b64 vcc, exec, s[4:5]
	v_mov_b32_e32 v62, 0
	v_mov_b32_e32 v63, 0
	v_mov_b32_e32 v64, 0
	v_mov_b32_e32 v65, 0
	s_cbranch_vccnz .LBB0_374
	v_lshl_add_u64 v[60:61], v[70:71], 0, v[66:67]
	v_add_co_u32_e32 v60, vcc, 0x70000, v60
	s_nop 1
	v_addc_co_u32_e32 v61, vcc, 0, v61, vcc
	global_load_dwordx4 v[62:65], v[60:61], off sc1 nt
.LBB0_374:
	s_and_b64 vcc, exec, s[4:5]
	v_mov_b32_e32 v59, 0
	v_mov_b32_e32 v60, 0
	v_mov_b32_e32 v61, 0
	s_cbranch_vccnz .LBB0_339
	v_lshl_add_u64 v[58:59], v[70:71], 0, v[66:67]
	v_add_co_u32_e32 v58, vcc, 0x78000, v58
	s_nop 1
	v_addc_co_u32_e32 v59, vcc, 0, v59, vcc
	global_load_dwordx4 v[58:61], v[58:59], off sc1 nt
	s_branch .LBB0_339

.LBB0_388:
	s_cmpk_gt_i32 s14, 0xbff
	s_mov_b64 s[2:3], -1
	s_cbranch_scc0 .LBB0_390
	s_bfe_u32 s4, s14, 0x10007
	s_and_b32 s2, s14, 0x7fffff00
	s_cmpk_eq_i32 s2, 0xc00
	s_cselect_b32 s2, 40, 64
	s_cselect_b32 s5, s20, 0x8710000
	s_add_u32 s2, s80, s2
	s_addc_u32 s3, s81, 0
	s_load_dwordx2 s[2:3], s[2:3], 0x0
	s_lshl_b32 s12, s4, 21
	v_mov_b32_e32 v69, v67
	s_waitcnt lgkmcnt(0)
	s_add_u32 s2, s2, s12
	s_addc_u32 s3, s3, 0
	s_and_b32 s12, s16, 0xc0
	s_add_u32 s5, s10, s5
	v_or_b32_e32 v2, s12, v73
	s_addc_u32 s13, s11, 0
	s_and_b32 s29, s18, 0x7c0
	v_or_b32_e32 v4, s29, v74
	v_lshlrev_b32_e32 v66, 2, v2
	v_lshl_add_u64 v[2:3], s[2:3], 0, v[66:67]
	v_lshlrev_b32_e32 v66, 10, v4
	v_lshl_add_u64 v[62:63], v[2:3], 0, v[66:67]
	v_add_co_u32_e32 v14, vcc, s21, v62
	global_load_dwordx4 v[2:5], v[62:63], off sc1 nt
	s_nop 0
	v_addc_co_u32_e32 v15, vcc, 0, v63, vcc
	v_add_co_u32_e32 v22, vcc, s22, v62
	global_load_dwordx4 v[6:9], v[14:15], off offset:-4096 sc1 nt
	global_load_dwordx4 v[10:13], v[14:15], off sc1 nt
	v_addc_co_u32_e32 v23, vcc, 0, v63, vcc
	v_add_co_u32_e32 v30, vcc, s23, v62
	global_load_dwordx4 v[14:17], v[22:23], off offset:-4096 sc1 nt
	global_load_dwordx4 v[18:21], v[22:23], off sc1 nt
	v_addc_co_u32_e32 v31, vcc, 0, v63, vcc
	v_add_co_u32_e32 v38, vcc, s24, v62
	global_load_dwordx4 v[22:25], v[30:31], off offset:-4096 sc1 nt
	global_load_dwordx4 v[26:29], v[30:31], off sc1 nt
	v_addc_co_u32_e32 v39, vcc, 0, v63, vcc
	v_add_co_u32_e32 v46, vcc, s25, v62
	global_load_dwordx4 v[30:33], v[38:39], off offset:-4096 sc1 nt
	global_load_dwordx4 v[34:37], v[38:39], off sc1 nt
	v_addc_co_u32_e32 v47, vcc, 0, v63, vcc
	v_add_co_u32_e32 v54, vcc, s26, v62
	global_load_dwordx4 v[38:41], v[46:47], off offset:-4096 sc1 nt
	global_load_dwordx4 v[42:45], v[46:47], off sc1 nt
	v_addc_co_u32_e32 v55, vcc, 0, v63, vcc
	v_add_co_u32_e32 v64, vcc, s27, v62
	global_load_dwordx4 v[46:49], v[54:55], off offset:-4096 sc1 nt
	global_load_dwordx4 v[50:53], v[54:55], off sc1 nt
	v_addc_co_u32_e32 v65, vcc, 0, v63, vcc
	global_load_dwordx4 v[54:57], v[64:65], off offset:-4096 sc1 nt
	global_load_dwordx4 v[58:61], v[64:65], off sc1 nt
	v_add_co_u32_e32 v62, vcc, s28, v62
	s_lshl_b32 s2, s4, 8
	s_nop 0
	v_addc_co_u32_e32 v63, vcc, 0, v63, vcc
	global_load_dwordx4 v[62:65], v[62:63], off sc1 nt
	s_or_b32 s4, s2, s12
	s_lshl_b32 s2, s29, 1
	s_add_u32 s2, s5, s2
	s_addc_u32 s3, s13, 0
	s_waitcnt vmcnt(15)
	ds_write2_b32 v75, v2, v3 offset1:1
	ds_write2_b32 v75, v4, v5 offset0:2 offset1:3
	s_waitcnt vmcnt(14)
	ds_write2_b32 v87, v6, v7 offset1:1
	ds_write2_b32 v88, v8, v9 offset1:1
	s_waitcnt vmcnt(13)
	ds_write2_b32 v89, v10, v11 offset1:1
	ds_write2_b32 v90, v12, v13 offset1:1
	s_waitcnt vmcnt(12)
	ds_write2_b32 v91, v14, v15 offset1:1
	ds_write2_b32 v92, v16, v17 offset1:1
	s_waitcnt vmcnt(11)
	ds_write2_b32 v93, v18, v19 offset1:1
	ds_write2_b32 v94, v20, v21 offset1:1
	s_waitcnt vmcnt(10)
	ds_write2_b32 v95, v22, v23 offset1:1
	ds_write2_b32 v96, v24, v25 offset1:1
	s_waitcnt vmcnt(9)
	ds_write2_b32 v97, v26, v27 offset1:1
	ds_write2_b32 v98, v28, v29 offset1:1
	s_waitcnt vmcnt(8)
	ds_write2_b32 v99, v30, v31 offset1:1
	ds_write2_b32 v100, v32, v33 offset1:1
	s_waitcnt vmcnt(7)
	ds_write2_b32 v101, v34, v35 offset1:1
	ds_write2_b32 v102, v36, v37 offset1:1
	s_waitcnt vmcnt(6)
	ds_write2_b32 v103, v38, v39 offset1:1
	ds_write2_b32 v104, v40, v41 offset1:1
	s_waitcnt vmcnt(5)
	ds_write2_b32 v105, v42, v43 offset1:1
	ds_write2_b32 v106, v44, v45 offset1:1
	s_waitcnt vmcnt(4)
	ds_write2_b32 v107, v46, v47 offset1:1
	ds_write2_b32 v108, v48, v49 offset1:1
	s_waitcnt vmcnt(3)
	ds_write2_b32 v109, v50, v51 offset1:1
	ds_write2_b32 v110, v52, v53 offset1:1
	s_waitcnt vmcnt(2)
	ds_write2_b32 v111, v54, v55 offset1:1
	ds_write2_b32 v112, v56, v57 offset1:1
	s_waitcnt vmcnt(1)
	ds_write2_b32 v113, v58, v59 offset1:1
	ds_write2_b32 v114, v60, v61 offset1:1
	s_waitcnt vmcnt(0)
	ds_write2_b32 v115, v62, v63 offset1:1
	ds_write2_b32 v116, v64, v65 offset1:1
	s_waitcnt lgkmcnt(0)
	ds_read2_b32 v[6:7], v77 offset0:65 offset1:73
	ds_read2_b32 v[8:9], v77 offset1:8
	ds_read2_b32 v[10:11], v77 offset0:130 offset1:138
	ds_read2_b32 v[12:13], v77 offset0:195 offset1:203
	ds_read2_b32 v[14:15], v86 offset0:4 offset1:12
	ds_read2_b32 v[16:17], v86 offset0:69 offset1:77
	ds_read2_b32 v[18:19], v86 offset0:134 offset1:142
	ds_read2_b32 v[20:21], v86 offset0:199 offset1:207
	s_waitcnt lgkmcnt(6)
	v_cvt_pk_bf16_f32 v2, v8, v6
	v_or_b32_e32 v6, s4, v76
	v_lshl_add_u64 v[22:23], s[2:3], 0, v[68:69]
	v_lshlrev_b32_e32 v66, 12, v6
	s_waitcnt lgkmcnt(4)
	v_cvt_pk_bf16_f32 v3, v10, v12
	s_waitcnt lgkmcnt(2)
	v_cvt_pk_bf16_f32 v4, v14, v16
	s_waitcnt lgkmcnt(0)
	v_cvt_pk_bf16_f32 v5, v18, v20
	v_lshl_add_u64 v[24:25], v[22:23], 0, v[66:67]
	global_store_dwordx4 v[24:25], v[2:5], off
	v_or_b32_e32 v6, s4, v78
	v_lshlrev_b32_e32 v66, 12, v6
	v_cvt_pk_bf16_f32 v2, v9, v7
	v_cvt_pk_bf16_f32 v3, v11, v13
	v_cvt_pk_bf16_f32 v4, v15, v17
	v_cvt_pk_bf16_f32 v5, v19, v21
	ds_read2_b32 v[8:9], v77 offset0:81 offset1:89
	ds_read2_b32 v[10:11], v77 offset0:16 offset1:24
	ds_read2_b32 v[12:13], v77 offset0:146 offset1:154
	ds_read2_b32 v[14:15], v77 offset0:211 offset1:219
	ds_read2_b32 v[16:17], v86 offset0:20 offset1:28
	ds_read2_b32 v[18:19], v86 offset0:85 offset1:93
	ds_read2_b32 v[20:21], v86 offset0:150 offset1:158
	ds_read2_b32 v[24:25], v86 offset0:215 offset1:223
	v_lshl_add_u64 v[6:7], v[22:23], 0, v[66:67]
	global_store_dwordx4 v[6:7], v[2:5], off
	v_or_b32_e32 v6, s4, v80
	v_lshlrev_b32_e32 v66, 12, v6
	s_waitcnt lgkmcnt(6)
	v_cvt_pk_bf16_f32 v2, v10, v8
	s_waitcnt lgkmcnt(4)
	v_cvt_pk_bf16_f32 v3, v12, v14
	s_waitcnt lgkmcnt(2)
	v_cvt_pk_bf16_f32 v4, v16, v18
	s_waitcnt lgkmcnt(0)
	v_cvt_pk_bf16_f32 v5, v20, v24
	v_lshl_add_u64 v[6:7], v[22:23], 0, v[66:67]
	global_store_dwordx4 v[6:7], v[2:5], off
	v_or_b32_e32 v6, s4, v81
	v_lshlrev_b32_e32 v66, 12, v6
	v_cvt_pk_bf16_f32 v2, v11, v9
	v_cvt_pk_bf16_f32 v3, v13, v15
	v_cvt_pk_bf16_f32 v4, v17, v19
	v_cvt_pk_bf16_f32 v5, v21, v25
	ds_read2_b32 v[8:9], v77 offset0:32 offset1:40
	ds_read2_b32 v[10:11], v77 offset0:97 offset1:105
	ds_read2_b32 v[12:13], v77 offset0:162 offset1:170
	ds_read2_b32 v[14:15], v77 offset0:227 offset1:235
	ds_read2_b32 v[16:17], v86 offset0:36 offset1:44
	ds_read2_b32 v[18:19], v86 offset0:101 offset1:109
	ds_read2_b32 v[20:21], v86 offset0:166 offset1:174
	ds_read2_b32 v[24:25], v86 offset0:231 offset1:239
	v_lshl_add_u64 v[6:7], v[22:23], 0, v[66:67]
	global_store_dwordx4 v[6:7], v[2:5], off
	v_or_b32_e32 v6, s4, v82
	v_lshlrev_b32_e32 v66, 12, v6
	s_waitcnt lgkmcnt(6)
	v_cvt_pk_bf16_f32 v2, v8, v10
	s_waitcnt lgkmcnt(4)
	v_cvt_pk_bf16_f32 v3, v12, v14
	s_waitcnt lgkmcnt(2)
	v_cvt_pk_bf16_f32 v4, v16, v18
	s_waitcnt lgkmcnt(0)
	v_cvt_pk_bf16_f32 v5, v20, v24
	v_lshl_add_u64 v[6:7], v[22:23], 0, v[66:67]
	global_store_dwordx4 v[6:7], v[2:5], off
	v_or_b32_e32 v6, s4, v83
	v_lshlrev_b32_e32 v66, 12, v6
	v_cvt_pk_bf16_f32 v2, v9, v11
	v_cvt_pk_bf16_f32 v3, v13, v15
	v_cvt_pk_bf16_f32 v4, v17, v19
	v_cvt_pk_bf16_f32 v5, v21, v25
	ds_read2_b32 v[8:9], v77 offset0:48 offset1:56
	ds_read2_b32 v[10:11], v77 offset0:113 offset1:121
	ds_read2_b32 v[12:13], v77 offset0:178 offset1:186
	ds_read2_b32 v[14:15], v77 offset0:243 offset1:251
	ds_read2_b32 v[16:17], v86 offset0:52 offset1:60
	ds_read2_b32 v[18:19], v86 offset0:117 offset1:125
	ds_read2_b32 v[20:21], v86 offset0:182 offset1:190
	ds_read2_b32 v[24:25], v86 offset0:247 offset1:255
	v_lshl_add_u64 v[6:7], v[22:23], 0, v[66:67]
	global_store_dwordx4 v[6:7], v[2:5], off
	v_or_b32_e32 v6, s4, v84
	v_lshlrev_b32_e32 v66, 12, v6
	s_waitcnt lgkmcnt(6)
	v_cvt_pk_bf16_f32 v2, v8, v10
	s_waitcnt lgkmcnt(4)
	v_cvt_pk_bf16_f32 v3, v12, v14
	s_waitcnt lgkmcnt(2)
	v_cvt_pk_bf16_f32 v4, v16, v18
	s_waitcnt lgkmcnt(0)
	v_cvt_pk_bf16_f32 v5, v20, v24
	v_lshl_add_u64 v[6:7], v[22:23], 0, v[66:67]
	global_store_dwordx4 v[6:7], v[2:5], off
	v_or_b32_e32 v6, s4, v85
	v_lshlrev_b32_e32 v66, 12, v6
	v_cvt_pk_bf16_f32 v2, v9, v11
	v_cvt_pk_bf16_f32 v3, v13, v15
	v_cvt_pk_bf16_f32 v4, v17, v19
	v_cvt_pk_bf16_f32 v5, v21, v25
	v_lshl_add_u64 v[6:7], v[22:23], 0, v[66:67]
	global_store_dwordx4 v[6:7], v[2:5], off
	s_waitcnt lgkmcnt(0)
	s_mov_b64 s[2:3], 0
.LBB0_390:
	s_andn2_b64 vcc, exec, s[2:3]
	s_cbranch_vccnz .LBB0_387
	s_ashr_i32 s2, s14, 31
	s_lshr_b32 s2, s2, 22
	s_add_i32 s3, s14, s2
	s_ashr_i32 s2, s3, 10
	s_and_b32 s3, s3, 0xfffffc00
	s_sub_i32 s31, s14, s3
	s_ashr_i32 s3, s2, 31
	s_lshl_b64 s[4:5], s[2:3], 3
	s_add_u32 s4, s80, s4
	s_addc_u32 s5, s81, s5
	s_load_dwordx2 s[4:5], s[4:5], 0x60
	s_lshl_b32 s12, s2, 11
	s_sub_i32 s29, s16, s12
	s_andn2_b32 s29, s29, 63
	s_and_b32 s30, s18, 0x7c0
	v_or_b32_e32 v66, s29, v73
	s_cmp_gt_i32 s31, -1
	v_or_b32_e32 v2, s30, v74
	s_cselect_b64 s[12:13], -1, 0
	s_cmp_lt_i32 s31, 0
	s_waitcnt lgkmcnt(0)
	v_lshl_add_u64 v[70:71], v[66:67], 2, s[4:5]
	v_mov_b32_e32 v6, 0
	v_lshlrev_b32_e32 v66, 13, v2
	v_mov_b32_e32 v2, 0
	v_mov_b32_e32 v3, 0
	v_mov_b32_e32 v4, 0
	v_mov_b32_e32 v5, 0
	s_cbranch_scc1 .LBB0_393
	v_lshl_add_u64 v[2:3], v[70:71], 0, v[66:67]
	global_load_dwordx4 v[2:5], v[2:3], off sc1 nt
.LBB0_393:
	v_cndmask_b32_e64 v7, 0, 1, s[12:13]
	v_cmp_ne_u32_e64 s[4:5], 1, v7
	s_andn2_b64 vcc, exec, s[12:13]
	v_mov_b32_e32 v7, 0
	v_mov_b32_e32 v8, 0
	v_mov_b32_e32 v9, 0
	s_cbranch_vccnz .LBB0_395
	v_lshl_add_u64 v[6:7], v[70:71], 0, v[66:67]
	v_add_co_u32_e32 v6, vcc, 0x8000, v6
	s_nop 1
	v_addc_co_u32_e32 v7, vcc, 0, v7, vcc
	global_load_dwordx4 v[6:9], v[6:7], off sc1 nt
